# tail split with specialised half-unit K-loops (other half's MFMA blocks and A-fragment reads removed, no guards)
# baseline (speedup 1.0000x reference)
.LBB0_1746:
	v_lshl_add_u64 v[200:201], v[0:1], 0, s[24:25]
	v_mov_b32_e32 v0, 0
	v_add_u32_e32 v214, -1, v193
	v_lshl_add_u64 v[202:203], v[2:3], 0, s[28:29]
	s_mov_b32 s51, -2
	v_mov_b32_e32 v180, v4
	v_mov_b32_e32 v1, v0
	v_mov_b32_e32 v2, v0
	v_mov_b32_e32 v3, v0
	v_mov_b32_e32 v8, v0
	v_mov_b32_e32 v9, v0
	v_mov_b32_e32 v10, v0
	v_mov_b32_e32 v11, v0
	v_mov_b32_e32 v16, v0
	v_mov_b32_e32 v17, v0
	v_mov_b32_e32 v18, v0
	v_mov_b32_e32 v19, v0
	v_mov_b32_e32 v24, v0
	v_mov_b32_e32 v25, v0
	v_mov_b32_e32 v26, v0
	v_mov_b32_e32 v27, v0
	v_mov_b32_e32 v32, v0
	v_mov_b32_e32 v33, v0
	v_mov_b32_e32 v34, v0
	v_mov_b32_e32 v35, v0
	v_mov_b32_e32 v40, v0
	v_mov_b32_e32 v41, v0
	v_mov_b32_e32 v42, v0
	v_mov_b32_e32 v43, v0
	v_mov_b32_e32 v48, v0
	v_mov_b32_e32 v49, v0
	v_mov_b32_e32 v50, v0
	v_mov_b32_e32 v51, v0
	v_mov_b32_e32 v56, v0
	v_mov_b32_e32 v57, v0
	v_mov_b32_e32 v58, v0
	v_mov_b32_e32 v59, v0
	v_mov_b32_e32 v4, v0
	v_mov_b32_e32 v5, v0
	v_mov_b32_e32 v6, v0
	v_mov_b32_e32 v7, v0
	v_mov_b32_e32 v12, v0
	v_mov_b32_e32 v13, v0
	v_mov_b32_e32 v14, v0
	v_mov_b32_e32 v15, v0
	v_mov_b32_e32 v20, v0
	v_mov_b32_e32 v21, v0
	v_mov_b32_e32 v22, v0
	v_mov_b32_e32 v23, v0
	v_mov_b32_e32 v28, v0
	v_mov_b32_e32 v29, v0
	v_mov_b32_e32 v30, v0
	v_mov_b32_e32 v31, v0
	v_mov_b32_e32 v36, v0
	v_mov_b32_e32 v37, v0
	v_mov_b32_e32 v38, v0
	v_mov_b32_e32 v39, v0
	v_mov_b32_e32 v44, v0
	v_mov_b32_e32 v45, v0
	v_mov_b32_e32 v46, v0
	v_mov_b32_e32 v47, v0
	v_mov_b32_e32 v52, v0
	v_mov_b32_e32 v53, v0
	v_mov_b32_e32 v54, v0
	v_mov_b32_e32 v55, v0
	v_mov_b32_e32 v60, v0
	v_mov_b32_e32 v61, v0
	v_mov_b32_e32 v62, v0
	v_mov_b32_e32 v63, v0
	v_mov_b32_e32 v64, v0
	v_mov_b32_e32 v65, v0
	v_mov_b32_e32 v66, v0
	v_mov_b32_e32 v67, v0
	v_mov_b32_e32 v72, v0
	v_mov_b32_e32 v73, v0
	v_mov_b32_e32 v74, v0
	v_mov_b32_e32 v75, v0
	v_mov_b32_e32 v80, v0
	v_mov_b32_e32 v81, v0
	v_mov_b32_e32 v82, v0
	v_mov_b32_e32 v83, v0
	v_mov_b32_e32 v88, v0
	v_mov_b32_e32 v89, v0
	v_mov_b32_e32 v90, v0
	v_mov_b32_e32 v91, v0
	v_mov_b32_e32 v96, v0
	v_mov_b32_e32 v97, v0
	v_mov_b32_e32 v98, v0
	v_mov_b32_e32 v99, v0
	v_mov_b32_e32 v104, v0
	v_mov_b32_e32 v105, v0
	v_mov_b32_e32 v106, v0
	v_mov_b32_e32 v107, v0
	v_mov_b32_e32 v112, v0
	v_mov_b32_e32 v113, v0
	v_mov_b32_e32 v114, v0
	v_mov_b32_e32 v115, v0
	v_mov_b32_e32 v120, v0
	v_mov_b32_e32 v121, v0
	v_mov_b32_e32 v122, v0
	v_mov_b32_e32 v123, v0
	v_mov_b32_e32 v68, v0
	v_mov_b32_e32 v69, v0
	v_mov_b32_e32 v70, v0
	v_mov_b32_e32 v71, v0
	v_mov_b32_e32 v76, v0
	v_mov_b32_e32 v77, v0
	v_mov_b32_e32 v78, v0
	v_mov_b32_e32 v79, v0
	v_mov_b32_e32 v84, v0
	v_mov_b32_e32 v85, v0
	v_mov_b32_e32 v86, v0
	v_mov_b32_e32 v87, v0
	v_mov_b32_e32 v92, v0
	v_mov_b32_e32 v93, v0
	v_mov_b32_e32 v94, v0
	v_mov_b32_e32 v95, v0
	v_mov_b32_e32 v100, v0
	v_mov_b32_e32 v101, v0
	v_mov_b32_e32 v102, v0
	v_mov_b32_e32 v103, v0
	v_mov_b32_e32 v108, v0
	v_mov_b32_e32 v109, v0
	v_mov_b32_e32 v110, v0
	v_mov_b32_e32 v111, v0
	v_mov_b32_e32 v116, v0
	v_mov_b32_e32 v117, v0
	v_mov_b32_e32 v118, v0
	v_mov_b32_e32 v119, v0
	v_mov_b32_e32 v124, v0
	v_mov_b32_e32 v125, v0
	v_mov_b32_e32 v126, v0
	v_mov_b32_e32 v127, v0
	s_cmp_eq_u32 s90, 3
	s_cbranch_scc1 .LBB0_1749
	s_cmp_eq_u32 s90, 1
	s_cbranch_scc1 .Lts_a0_h
	s_branch .Lts_a1_h

.Lts_a0_b:
	s_waitcnt lgkmcnt(8)
	s_barrier
	s_waitcnt lgkmcnt(0)
	v_lshl_add_u64 v[206:207], v[200:201], 0, s[24:25]
	v_cndmask_b32_e64 v233, v207, v195, s[8:9]
	v_cndmask_b32_e64 v232, v206, v194, s[8:9]
	v_cndmask_b32_e64 v207, v203, v197, s[8:9]
	v_cndmask_b32_e64 v206, v202, v196, s[8:9]
	s_setprio 1
	s_waitcnt lgkmcnt(0)
	v_mfma_f32_16x16x32_bf16 v[124:127], v[128:131], v[168:171], v[124:127]
	v_mfma_f32_16x16x32_bf16 v[116:119], v[136:139], v[168:171], v[116:119]
	v_mfma_f32_16x16x32_bf16 v[108:111], v[128:131], v[160:163], v[108:111]
	v_mfma_f32_16x16x32_bf16 v[100:103], v[136:139], v[160:163], v[100:103]
	v_mfma_f32_16x16x32_bf16 v[92:95], v[128:131], v[152:155], v[92:95]
	v_mfma_f32_16x16x32_bf16 v[84:87], v[136:139], v[152:155], v[84:87]
	v_mfma_f32_16x16x32_bf16 v[76:79], v[128:131], v[144:147], v[76:79]
	v_mfma_f32_16x16x32_bf16 v[68:71], v[136:139], v[144:147], v[68:71]
	v_mfma_f32_16x16x32_bf16 v[124:127], v[132:135], v[172:175], v[124:127]
	v_mfma_f32_16x16x32_bf16 v[116:119], v[140:143], v[172:175], v[116:119]
	v_mfma_f32_16x16x32_bf16 v[108:111], v[132:135], v[164:167], v[108:111]
	v_mfma_f32_16x16x32_bf16 v[100:103], v[140:143], v[164:167], v[100:103]
	v_mfma_f32_16x16x32_bf16 v[92:95], v[132:135], v[156:159], v[92:95]
	v_mfma_f32_16x16x32_bf16 v[84:87], v[140:143], v[156:159], v[84:87]
	v_mfma_f32_16x16x32_bf16 v[76:79], v[132:135], v[148:151], v[76:79]
	v_mfma_f32_16x16x32_bf16 v[68:71], v[140:143], v[148:151], v[68:71]
	s_setprio 0
	s_barrier
	s_mov_b32 m0, s62
	v_add_u32_e32 v185, s77, v211
	v_lshl_add_u64 v[234:235], v[206:207], 0, v[176:177]
	ds_read_b128 v[216:219], v185
	ds_read_b128 v[220:223], v185 offset:1024
	ds_read_b128 v[224:227], v185 offset:2048
	ds_read_b128 v[228:231], v185 offset:3072
	global_load_lds_dwordx4 v[234:235], off
	v_lshl_add_u64 v[236:237], v[206:207], 0, v[178:179]
	s_mov_b32 m0, s64
	s_nop 0
	global_load_lds_dwordx4 v[236:237], off
	s_barrier
	s_waitcnt lgkmcnt(0)
	s_setprio 1
	s_waitcnt lgkmcnt(0)
	v_mfma_f32_16x16x32_bf16 v[120:123], v[216:219], v[168:171], v[120:123]
	v_mfma_f32_16x16x32_bf16 v[112:115], v[224:227], v[168:171], v[112:115]
	v_mfma_f32_16x16x32_bf16 v[104:107], v[216:219], v[160:163], v[104:107]
	v_mfma_f32_16x16x32_bf16 v[96:99], v[224:227], v[160:163], v[96:99]
	v_mfma_f32_16x16x32_bf16 v[88:91], v[216:219], v[152:155], v[88:91]
	v_mfma_f32_16x16x32_bf16 v[80:83], v[224:227], v[152:155], v[80:83]
	v_mfma_f32_16x16x32_bf16 v[72:75], v[216:219], v[144:147], v[72:75]
	v_mfma_f32_16x16x32_bf16 v[64:67], v[224:227], v[144:147], v[64:67]
	v_mfma_f32_16x16x32_bf16 v[120:123], v[220:223], v[172:175], v[120:123]
	v_mfma_f32_16x16x32_bf16 v[112:115], v[228:231], v[172:175], v[112:115]
	v_mfma_f32_16x16x32_bf16 v[104:107], v[220:223], v[164:167], v[104:107]
	v_mfma_f32_16x16x32_bf16 v[96:99], v[228:231], v[164:167], v[96:99]
	v_mfma_f32_16x16x32_bf16 v[88:91], v[220:223], v[156:159], v[88:91]
	v_mfma_f32_16x16x32_bf16 v[80:83], v[228:231], v[156:159], v[80:83]
	v_mfma_f32_16x16x32_bf16 v[72:75], v[220:223], v[148:151], v[72:75]
	v_mfma_f32_16x16x32_bf16 v[64:67], v[228:231], v[148:151], v[64:67]
	s_setprio 0
	s_mov_b32 m0, s61
	v_readfirstlane_b32 s8, v232
	v_readfirstlane_b32 s9, v233
	s_barrier
	s_nop 7
	global_load_lds_dwordx4 v180, s[8:9]
	s_mov_b32 m0, s65
	v_mov_b32_e32 v185, v181
	global_load_lds_dwordx4 v184, s[8:9]
	s_barrier
	s_waitcnt lgkmcnt(0)
	v_lshl_add_u64 v[238:239], v[232:233], 0, v[180:181]
	v_lshl_add_u64 v[240:241], v[232:233], 0, v[184:185]
	s_setprio 1
	s_waitcnt lgkmcnt(0)
	s_setprio 0
	s_barrier
	v_lshl_add_u64 v[128:129], v[206:207], 0, s[22:23]
	s_add_i32 s8, s77, s60
	v_lshl_add_u64 v[130:131], v[128:129], 0, v[176:177]
	s_mov_b32 m0, s8
	v_lshl_add_u64 v[128:129], v[128:129], 0, v[178:179]
	global_load_lds_dwordx4 v[130:131], off
	s_add_i32 m0, s8, 0x2000
	s_nop 0
	global_load_lds_dwordx4 v[128:129], off
	s_waitcnt vmcnt(6)
	s_barrier
	s_setprio 1
	s_setprio 0
	s_add_i32 s8, 0, 0x18000
	v_add_u32_e32 v140, s8, v211
	s_barrier
	ds_read_b128 v[128:131], v140
	ds_read_b128 v[132:135], v140 offset:1024
	ds_read_b128 v[136:139], v140 offset:2048
	ds_read_b128 v[140:143], v140 offset:3072
	s_mov_b32 m0, s66
	v_lshl_add_u64 v[204:205], v[232:233], 0, v[204:205]
	ds_read_b128 v[144:147], v213 offset:32768
	ds_read_b128 v[148:151], v213 offset:33792
	ds_read_b128 v[152:155], v213 offset:34816
	ds_read_b128 v[156:159], v213 offset:35840
	ds_read_b128 v[160:163], v213 offset:36864
	ds_read_b128 v[164:167], v213 offset:37888
	ds_read_b128 v[168:171], v213 offset:38912
	ds_read_b128 v[172:175], v213 offset:39936
	global_load_lds_dwordx4 v[204:205], off
	v_lshl_add_u64 v[204:205], v[232:233], 0, v[182:183]
	s_mov_b32 m0, s67
	s_nop 0
	global_load_lds_dwordx4 v[204:205], off
	s_waitcnt lgkmcnt(8)
	s_barrier
	s_waitcnt lgkmcnt(0)
	s_setprio 1
	s_waitcnt lgkmcnt(0)
	v_mfma_f32_16x16x32_bf16 v[124:127], v[128:131], v[144:147], v[124:127]
	v_mfma_f32_16x16x32_bf16 v[116:119], v[136:139], v[144:147], v[116:119]
	v_mfma_f32_16x16x32_bf16 v[108:111], v[128:131], v[152:155], v[108:111]
	v_mfma_f32_16x16x32_bf16 v[100:103], v[136:139], v[152:155], v[100:103]
	v_mfma_f32_16x16x32_bf16 v[92:95], v[128:131], v[160:163], v[92:95]
	v_mfma_f32_16x16x32_bf16 v[84:87], v[136:139], v[160:163], v[84:87]
	v_mfma_f32_16x16x32_bf16 v[76:79], v[128:131], v[168:171], v[76:79]
	v_mfma_f32_16x16x32_bf16 v[68:71], v[136:139], v[168:171], v[68:71]
	v_mfma_f32_16x16x32_bf16 v[124:127], v[132:135], v[148:151], v[124:127]
	v_mfma_f32_16x16x32_bf16 v[116:119], v[140:143], v[148:151], v[116:119]
	v_mfma_f32_16x16x32_bf16 v[108:111], v[132:135], v[156:159], v[108:111]
	v_mfma_f32_16x16x32_bf16 v[100:103], v[140:143], v[156:159], v[100:103]
	v_mfma_f32_16x16x32_bf16 v[92:95], v[132:135], v[164:167], v[92:95]
	v_mfma_f32_16x16x32_bf16 v[84:87], v[140:143], v[164:167], v[84:87]
	v_mfma_f32_16x16x32_bf16 v[76:79], v[132:135], v[172:175], v[76:79]
	v_mfma_f32_16x16x32_bf16 v[68:71], v[140:143], v[172:175], v[68:71]
	s_setprio 0
	s_barrier
	s_add_i32 s9, 0, 0x1c000
	s_add_i32 s8, s8, s60
	v_add_u32_e32 v183, s9, v211
	v_lshl_add_u64 v[204:205], v[234:235], 0, s[24:25]
	s_mov_b32 m0, s8
	ds_read_b128 v[216:219], v183
	ds_read_b128 v[220:223], v183 offset:1024
	ds_read_b128 v[224:227], v183 offset:2048
	ds_read_b128 v[228:231], v183 offset:3072
	global_load_lds_dwordx4 v[204:205], off
	v_lshl_add_u64 v[204:205], v[236:237], 0, s[24:25]
	s_add_i32 m0, s8, 0x2000
	s_nop 0
	global_load_lds_dwordx4 v[204:205], off
	s_barrier
	s_waitcnt lgkmcnt(0)
	s_setprio 1
	s_waitcnt lgkmcnt(0)
	v_mfma_f32_16x16x32_bf16 v[120:123], v[216:219], v[144:147], v[120:123]
	v_mfma_f32_16x16x32_bf16 v[112:115], v[224:227], v[144:147], v[112:115]
	v_mfma_f32_16x16x32_bf16 v[104:107], v[216:219], v[152:155], v[104:107]
	v_mfma_f32_16x16x32_bf16 v[96:99], v[224:227], v[152:155], v[96:99]
	v_mfma_f32_16x16x32_bf16 v[88:91], v[216:219], v[160:163], v[88:91]
	v_mfma_f32_16x16x32_bf16 v[80:83], v[224:227], v[160:163], v[80:83]
	v_mfma_f32_16x16x32_bf16 v[72:75], v[216:219], v[168:171], v[72:75]
	v_mfma_f32_16x16x32_bf16 v[64:67], v[224:227], v[168:171], v[64:67]
	v_mfma_f32_16x16x32_bf16 v[120:123], v[220:223], v[148:151], v[120:123]
	v_mfma_f32_16x16x32_bf16 v[112:115], v[228:231], v[148:151], v[112:115]
	v_mfma_f32_16x16x32_bf16 v[104:107], v[220:223], v[156:159], v[104:107]
	v_mfma_f32_16x16x32_bf16 v[96:99], v[228:231], v[156:159], v[96:99]
	v_mfma_f32_16x16x32_bf16 v[88:91], v[220:223], v[164:167], v[88:91]
	v_mfma_f32_16x16x32_bf16 v[80:83], v[228:231], v[164:167], v[80:83]
	v_mfma_f32_16x16x32_bf16 v[72:75], v[220:223], v[172:175], v[72:75]
	v_mfma_f32_16x16x32_bf16 v[64:67], v[228:231], v[172:175], v[64:67]
	s_setprio 0
	s_mov_b32 m0, s70
	v_lshl_add_u64 v[204:205], v[238:239], 0, s[24:25]
	s_barrier
	s_nop 7
	global_load_lds_dwordx4 v[204:205], off
	v_lshl_add_u64 v[204:205], v[240:241], 0, s[24:25]
	s_mov_b32 m0, s71
	s_nop 0
	global_load_lds_dwordx4 v[204:205], off
	s_barrier
	s_waitcnt lgkmcnt(0)
	s_setprio 1
	s_waitcnt lgkmcnt(0)
	s_setprio 0
	s_barrier
	v_lshl_add_u64 v[128:129], v[206:207], 0, s[26:27]
	s_add_i32 s8, s9, s60
	v_lshl_add_u64 v[130:131], v[128:129], 0, v[176:177]
	s_mov_b32 m0, s8
	v_lshl_add_u64 v[128:129], v[128:129], 0, v[178:179]
	global_load_lds_dwordx4 v[130:131], off
	s_add_i32 m0, s8, 0x2000
	s_nop 0
	global_load_lds_dwordx4 v[128:129], off
	s_waitcnt vmcnt(6)
	s_barrier
	s_setprio 1
	s_setprio 0
	s_add_i32 s51, s51, 2
	v_lshl_add_u64 v[200:201], v[200:201], 0, s[28:29]
	s_cmp_gt_u32 s51, 29
	v_lshl_add_u64 v[202:203], v[202:203], 0, s[28:29]
	s_barrier
	s_cbranch_scc1 .LBB0_1732

.Lts_a1_b:
	s_waitcnt lgkmcnt(8)
	s_barrier
	s_waitcnt lgkmcnt(0)
	v_lshl_add_u64 v[206:207], v[200:201], 0, s[24:25]
	v_cndmask_b32_e64 v233, v207, v195, s[8:9]
	v_cndmask_b32_e64 v232, v206, v194, s[8:9]
	v_cndmask_b32_e64 v207, v203, v197, s[8:9]
	v_cndmask_b32_e64 v206, v202, v196, s[8:9]
	s_setprio 1
	s_waitcnt lgkmcnt(0)
	s_setprio 0
	s_barrier
	s_mov_b32 m0, s62
	v_add_u32_e32 v185, s77, v211
	v_lshl_add_u64 v[234:235], v[206:207], 0, v[176:177]
	ds_read_b128 v[216:219], v185
	ds_read_b128 v[220:223], v185 offset:1024
	ds_read_b128 v[224:227], v185 offset:2048
	ds_read_b128 v[228:231], v185 offset:3072
	global_load_lds_dwordx4 v[234:235], off
	v_lshl_add_u64 v[236:237], v[206:207], 0, v[178:179]
	s_mov_b32 m0, s64
	s_nop 0
	global_load_lds_dwordx4 v[236:237], off
	s_barrier
	s_waitcnt lgkmcnt(0)
	s_setprio 1
	s_waitcnt lgkmcnt(0)
	s_setprio 0
	s_mov_b32 m0, s61
	v_readfirstlane_b32 s8, v232
	v_readfirstlane_b32 s9, v233
	s_barrier
	ds_read_b128 v[144:147], v213 offset:16384
	ds_read_b128 v[148:151], v213 offset:17408
	ds_read_b128 v[152:155], v213 offset:18432
	ds_read_b128 v[156:159], v213 offset:19456
	ds_read_b128 v[160:163], v213 offset:20480
	ds_read_b128 v[164:167], v213 offset:21504
	ds_read_b128 v[168:171], v213 offset:22528
	ds_read_b128 v[172:175], v213 offset:23552
	global_load_lds_dwordx4 v180, s[8:9]
	s_mov_b32 m0, s65
	v_mov_b32_e32 v185, v181
	global_load_lds_dwordx4 v184, s[8:9]
	s_barrier
	s_waitcnt lgkmcnt(0)
	v_lshl_add_u64 v[238:239], v[232:233], 0, v[180:181]
	v_lshl_add_u64 v[240:241], v[232:233], 0, v[184:185]
	s_setprio 1
	s_waitcnt lgkmcnt(0)
	v_mfma_f32_16x16x32_bf16 v[60:63], v[128:131], v[144:147], v[60:63]
	v_mfma_f32_16x16x32_bf16 v[52:55], v[136:139], v[144:147], v[52:55]
	v_mfma_f32_16x16x32_bf16 v[44:47], v[128:131], v[152:155], v[44:47]
	v_mfma_f32_16x16x32_bf16 v[36:39], v[136:139], v[152:155], v[36:39]
	v_mfma_f32_16x16x32_bf16 v[28:31], v[128:131], v[160:163], v[28:31]
	v_mfma_f32_16x16x32_bf16 v[20:23], v[136:139], v[160:163], v[20:23]
	v_mfma_f32_16x16x32_bf16 v[12:15], v[128:131], v[168:171], v[12:15]
	v_mfma_f32_16x16x32_bf16 v[4:7], v[136:139], v[168:171], v[4:7]
	v_mfma_f32_16x16x32_bf16 v[60:63], v[132:135], v[148:151], v[60:63]
	v_mfma_f32_16x16x32_bf16 v[52:55], v[140:143], v[148:151], v[52:55]
	v_mfma_f32_16x16x32_bf16 v[44:47], v[132:135], v[156:159], v[44:47]
	v_mfma_f32_16x16x32_bf16 v[36:39], v[140:143], v[156:159], v[36:39]
	v_mfma_f32_16x16x32_bf16 v[28:31], v[132:135], v[164:167], v[28:31]
	v_mfma_f32_16x16x32_bf16 v[20:23], v[140:143], v[164:167], v[20:23]
	v_mfma_f32_16x16x32_bf16 v[12:15], v[132:135], v[172:175], v[12:15]
	v_mfma_f32_16x16x32_bf16 v[4:7], v[140:143], v[172:175], v[4:7]
	s_setprio 0
	s_barrier
	v_lshl_add_u64 v[128:129], v[206:207], 0, s[22:23]
	s_add_i32 s8, s77, s60
	v_lshl_add_u64 v[130:131], v[128:129], 0, v[176:177]
	s_mov_b32 m0, s8
	v_lshl_add_u64 v[128:129], v[128:129], 0, v[178:179]
	global_load_lds_dwordx4 v[130:131], off
	s_add_i32 m0, s8, 0x2000
	s_nop 0
	global_load_lds_dwordx4 v[128:129], off
	s_waitcnt vmcnt(6)
	s_barrier
	s_setprio 1
	v_mfma_f32_16x16x32_bf16 v[56:59], v[216:219], v[144:147], v[56:59]
	v_mfma_f32_16x16x32_bf16 v[48:51], v[224:227], v[144:147], v[48:51]
	v_mfma_f32_16x16x32_bf16 v[40:43], v[216:219], v[152:155], v[40:43]
	v_mfma_f32_16x16x32_bf16 v[32:35], v[224:227], v[152:155], v[32:35]
	v_mfma_f32_16x16x32_bf16 v[24:27], v[216:219], v[160:163], v[24:27]
	v_mfma_f32_16x16x32_bf16 v[16:19], v[224:227], v[160:163], v[16:19]
	v_mfma_f32_16x16x32_bf16 v[8:11], v[216:219], v[168:171], v[8:11]
	v_mfma_f32_16x16x32_bf16 v[0:3], v[224:227], v[168:171], v[0:3]
	v_mfma_f32_16x16x32_bf16 v[56:59], v[220:223], v[148:151], v[56:59]
	v_mfma_f32_16x16x32_bf16 v[48:51], v[228:231], v[148:151], v[48:51]
	v_mfma_f32_16x16x32_bf16 v[40:43], v[220:223], v[156:159], v[40:43]
	v_mfma_f32_16x16x32_bf16 v[32:35], v[228:231], v[156:159], v[32:35]
	v_mfma_f32_16x16x32_bf16 v[24:27], v[220:223], v[164:167], v[24:27]
	v_mfma_f32_16x16x32_bf16 v[16:19], v[228:231], v[164:167], v[16:19]
	v_mfma_f32_16x16x32_bf16 v[8:11], v[220:223], v[172:175], v[8:11]
	v_mfma_f32_16x16x32_bf16 v[0:3], v[228:231], v[172:175], v[0:3]
	s_setprio 0
	s_add_i32 s8, 0, 0x18000
	v_add_u32_e32 v140, s8, v211
	s_barrier
	ds_read_b128 v[128:131], v140
	ds_read_b128 v[132:135], v140 offset:1024
	ds_read_b128 v[136:139], v140 offset:2048
	ds_read_b128 v[140:143], v140 offset:3072
	s_mov_b32 m0, s66
	v_lshl_add_u64 v[204:205], v[232:233], 0, v[204:205]
	s_nop 7
	global_load_lds_dwordx4 v[204:205], off
	v_lshl_add_u64 v[204:205], v[232:233], 0, v[182:183]
	s_mov_b32 m0, s67
	s_nop 0
	global_load_lds_dwordx4 v[204:205], off
	s_waitcnt lgkmcnt(8)
	s_barrier
	s_waitcnt lgkmcnt(0)
	s_setprio 1
	s_waitcnt lgkmcnt(0)
	s_setprio 0
	s_barrier
	s_add_i32 s9, 0, 0x1c000
	s_add_i32 s8, s8, s60
	v_add_u32_e32 v183, s9, v211
	v_lshl_add_u64 v[204:205], v[234:235], 0, s[24:25]
	s_mov_b32 m0, s8
	ds_read_b128 v[216:219], v183
	ds_read_b128 v[220:223], v183 offset:1024
	ds_read_b128 v[224:227], v183 offset:2048
	ds_read_b128 v[228:231], v183 offset:3072
	global_load_lds_dwordx4 v[204:205], off
	v_lshl_add_u64 v[204:205], v[236:237], 0, s[24:25]
	s_add_i32 m0, s8, 0x2000
	s_nop 0
	global_load_lds_dwordx4 v[204:205], off
	s_barrier
	s_waitcnt lgkmcnt(0)
	s_setprio 1
	s_waitcnt lgkmcnt(0)
	s_setprio 0
	s_mov_b32 m0, s70
	v_lshl_add_u64 v[204:205], v[238:239], 0, s[24:25]
	s_barrier
	ds_read_b128 v[144:147], v213 offset:49152
	ds_read_b128 v[148:151], v213 offset:50176
	ds_read_b128 v[152:155], v213 offset:51200
	ds_read_b128 v[156:159], v213 offset:52224
	ds_read_b128 v[160:163], v213 offset:53248
	ds_read_b128 v[164:167], v213 offset:54272
	ds_read_b128 v[168:171], v213 offset:55296
	ds_read_b128 v[172:175], v213 offset:56320
	global_load_lds_dwordx4 v[204:205], off
	v_lshl_add_u64 v[204:205], v[240:241], 0, s[24:25]
	s_mov_b32 m0, s71
	s_nop 0
	global_load_lds_dwordx4 v[204:205], off
	s_barrier
	s_waitcnt lgkmcnt(0)
	s_setprio 1
	s_waitcnt lgkmcnt(0)
	v_mfma_f32_16x16x32_bf16 v[60:63], v[128:131], v[144:147], v[60:63]
	v_mfma_f32_16x16x32_bf16 v[52:55], v[136:139], v[144:147], v[52:55]
	v_mfma_f32_16x16x32_bf16 v[44:47], v[128:131], v[152:155], v[44:47]
	v_mfma_f32_16x16x32_bf16 v[36:39], v[136:139], v[152:155], v[36:39]
	v_mfma_f32_16x16x32_bf16 v[28:31], v[128:131], v[160:163], v[28:31]
	v_mfma_f32_16x16x32_bf16 v[20:23], v[136:139], v[160:163], v[20:23]
	v_mfma_f32_16x16x32_bf16 v[12:15], v[128:131], v[168:171], v[12:15]
	v_mfma_f32_16x16x32_bf16 v[4:7], v[136:139], v[168:171], v[4:7]
	v_mfma_f32_16x16x32_bf16 v[60:63], v[132:135], v[148:151], v[60:63]
	v_mfma_f32_16x16x32_bf16 v[52:55], v[140:143], v[148:151], v[52:55]
	v_mfma_f32_16x16x32_bf16 v[44:47], v[132:135], v[156:159], v[44:47]
	v_mfma_f32_16x16x32_bf16 v[36:39], v[140:143], v[156:159], v[36:39]
	v_mfma_f32_16x16x32_bf16 v[28:31], v[132:135], v[164:167], v[28:31]
	v_mfma_f32_16x16x32_bf16 v[20:23], v[140:143], v[164:167], v[20:23]
	v_mfma_f32_16x16x32_bf16 v[12:15], v[132:135], v[172:175], v[12:15]
	v_mfma_f32_16x16x32_bf16 v[4:7], v[140:143], v[172:175], v[4:7]
	s_setprio 0
	s_barrier
	v_lshl_add_u64 v[128:129], v[206:207], 0, s[26:27]
	s_add_i32 s8, s9, s60
	v_lshl_add_u64 v[130:131], v[128:129], 0, v[176:177]
	s_mov_b32 m0, s8
	v_lshl_add_u64 v[128:129], v[128:129], 0, v[178:179]
	global_load_lds_dwordx4 v[130:131], off
	s_add_i32 m0, s8, 0x2000
	s_nop 0
	global_load_lds_dwordx4 v[128:129], off
	s_waitcnt vmcnt(6)
	s_barrier
	s_setprio 1
	v_mfma_f32_16x16x32_bf16 v[56:59], v[216:219], v[144:147], v[56:59]
	v_mfma_f32_16x16x32_bf16 v[48:51], v[224:227], v[144:147], v[48:51]
	v_mfma_f32_16x16x32_bf16 v[40:43], v[216:219], v[152:155], v[40:43]
	v_mfma_f32_16x16x32_bf16 v[32:35], v[224:227], v[152:155], v[32:35]
	v_mfma_f32_16x16x32_bf16 v[24:27], v[216:219], v[160:163], v[24:27]
	v_mfma_f32_16x16x32_bf16 v[16:19], v[224:227], v[160:163], v[16:19]
	v_mfma_f32_16x16x32_bf16 v[8:11], v[216:219], v[168:171], v[8:11]
	v_mfma_f32_16x16x32_bf16 v[0:3], v[224:227], v[168:171], v[0:3]
	v_mfma_f32_16x16x32_bf16 v[56:59], v[220:223], v[148:151], v[56:59]
	v_mfma_f32_16x16x32_bf16 v[48:51], v[228:231], v[148:151], v[48:51]
	v_mfma_f32_16x16x32_bf16 v[40:43], v[220:223], v[156:159], v[40:43]
	v_mfma_f32_16x16x32_bf16 v[32:35], v[228:231], v[156:159], v[32:35]
	v_mfma_f32_16x16x32_bf16 v[24:27], v[220:223], v[164:167], v[24:27]
	v_mfma_f32_16x16x32_bf16 v[16:19], v[228:231], v[164:167], v[16:19]
	v_mfma_f32_16x16x32_bf16 v[8:11], v[220:223], v[172:175], v[8:11]
	v_mfma_f32_16x16x32_bf16 v[0:3], v[228:231], v[172:175], v[0:3]
	s_setprio 0
	s_add_i32 s51, s51, 2
	v_lshl_add_u64 v[200:201], v[200:201], 0, s[28:29]
	s_cmp_gt_u32 s51, 29
	v_lshl_add_u64 v[202:203], v[202:203], 0, s[28:29]
	s_barrier
	s_cbranch_scc1 .LBB0_1732
.Lts_a1_h:
	v_add_u32_e32 v128, 0, v211
	v_add_u32_e32 v140, 0x10000, v128
	ds_read_b128 v[128:131], v140
	ds_read_b128 v[132:135], v140 offset:1024
	ds_read_b128 v[136:139], v140 offset:2048
	ds_read_b128 v[140:143], v140 offset:3072
	s_cmp_eq_u32 s51, 28
	s_cselect_b64 s[8:9], -1, 0
	s_add_i32 m0, s61, 0xc000
	v_readfirstlane_b32 s52, v200
	v_readfirstlane_b32 s53, v201
	s_nop 7
	global_load_lds_dwordx4 v186, s[52:53]
	s_add_i32 m0, s61, 0xe000
	s_nop 0
	global_load_lds_dwordx4 v182, s[52:53]
	s_and_b64 s[52:53], s[6:7], s[8:9]
	s_andn2_b64 vcc, exec, s[52:53]
	s_cbranch_vccz .Lts_a1_g
	v_mov_b32_e32 v187, v181
	v_mov_b32_e32 v183, v181
	v_mov_b64_e32 v[204:205], v[186:187]
	s_branch .Lts_a1_b

.LBB0_1831:
	v_lshl_add_u64 v[150:151], v[0:1], 0, s[20:21]
	v_mov_b32_e32 v0, 0
	v_lshl_add_u64 v[148:149], v[2:3], 0, s[18:19]
	s_mov_b32 s44, -2
	v_mov_b32_e32 v1, v0
	v_mov_b32_e32 v2, v0
	v_mov_b32_e32 v3, v0
	v_mov_b32_e32 v4, v0
	v_mov_b32_e32 v5, v0
	v_mov_b32_e32 v6, v0
	v_mov_b32_e32 v7, v0
	v_mov_b32_e32 v8, v0
	v_mov_b32_e32 v9, v0
	v_mov_b32_e32 v10, v0
	v_mov_b32_e32 v11, v0
	v_mov_b32_e32 v16, v0
	v_mov_b32_e32 v17, v0
	v_mov_b32_e32 v18, v0
	v_mov_b32_e32 v19, v0
	v_mov_b32_e32 v24, v0
	v_mov_b32_e32 v25, v0
	v_mov_b32_e32 v26, v0
	v_mov_b32_e32 v27, v0
	v_mov_b32_e32 v32, v0
	v_mov_b32_e32 v33, v0
	v_mov_b32_e32 v34, v0
	v_mov_b32_e32 v35, v0
	v_mov_b32_e32 v40, v0
	v_mov_b32_e32 v41, v0
	v_mov_b32_e32 v42, v0
	v_mov_b32_e32 v43, v0
	v_mov_b32_e32 v48, v0
	v_mov_b32_e32 v49, v0
	v_mov_b32_e32 v50, v0
	v_mov_b32_e32 v51, v0
	v_mov_b32_e32 v12, v0
	v_mov_b32_e32 v13, v0
	v_mov_b32_e32 v14, v0
	v_mov_b32_e32 v15, v0
	v_mov_b32_e32 v20, v0
	v_mov_b32_e32 v21, v0
	v_mov_b32_e32 v22, v0
	v_mov_b32_e32 v23, v0
	v_mov_b32_e32 v28, v0
	v_mov_b32_e32 v29, v0
	v_mov_b32_e32 v30, v0
	v_mov_b32_e32 v31, v0
	v_mov_b32_e32 v36, v0
	v_mov_b32_e32 v37, v0
	v_mov_b32_e32 v38, v0
	v_mov_b32_e32 v39, v0
	v_mov_b32_e32 v44, v0
	v_mov_b32_e32 v45, v0
	v_mov_b32_e32 v46, v0
	v_mov_b32_e32 v47, v0
	v_mov_b32_e32 v52, v0
	v_mov_b32_e32 v53, v0
	v_mov_b32_e32 v54, v0
	v_mov_b32_e32 v55, v0
	v_mov_b32_e32 v56, v0
	v_mov_b32_e32 v57, v0
	v_mov_b32_e32 v58, v0
	v_mov_b32_e32 v59, v0
	v_mov_b32_e32 v60, v0
	v_mov_b32_e32 v61, v0
	v_mov_b32_e32 v62, v0
	v_mov_b32_e32 v63, v0
	v_mov_b32_e32 v64, v0
	v_mov_b32_e32 v65, v0
	v_mov_b32_e32 v66, v0
	v_mov_b32_e32 v67, v0
	v_mov_b32_e32 v68, v0
	v_mov_b32_e32 v69, v0
	v_mov_b32_e32 v70, v0
	v_mov_b32_e32 v71, v0
	v_mov_b32_e32 v72, v0
	v_mov_b32_e32 v73, v0
	v_mov_b32_e32 v74, v0
	v_mov_b32_e32 v75, v0
	v_mov_b32_e32 v80, v0
	v_mov_b32_e32 v81, v0
	v_mov_b32_e32 v82, v0
	v_mov_b32_e32 v83, v0
	v_mov_b32_e32 v88, v0
	v_mov_b32_e32 v89, v0
	v_mov_b32_e32 v90, v0
	v_mov_b32_e32 v91, v0
	v_mov_b32_e32 v96, v0
	v_mov_b32_e32 v97, v0
	v_mov_b32_e32 v98, v0
	v_mov_b32_e32 v99, v0
	v_mov_b32_e32 v104, v0
	v_mov_b32_e32 v105, v0
	v_mov_b32_e32 v106, v0
	v_mov_b32_e32 v107, v0
	v_mov_b32_e32 v112, v0
	v_mov_b32_e32 v113, v0
	v_mov_b32_e32 v114, v0
	v_mov_b32_e32 v115, v0
	v_mov_b32_e32 v76, v0
	v_mov_b32_e32 v77, v0
	v_mov_b32_e32 v78, v0
	v_mov_b32_e32 v79, v0
	v_mov_b32_e32 v84, v0
	v_mov_b32_e32 v85, v0
	v_mov_b32_e32 v86, v0
	v_mov_b32_e32 v87, v0
	v_mov_b32_e32 v92, v0
	v_mov_b32_e32 v93, v0
	v_mov_b32_e32 v94, v0
	v_mov_b32_e32 v95, v0
	v_mov_b32_e32 v100, v0
	v_mov_b32_e32 v101, v0
	v_mov_b32_e32 v102, v0
	v_mov_b32_e32 v103, v0
	v_mov_b32_e32 v108, v0
	v_mov_b32_e32 v109, v0
	v_mov_b32_e32 v110, v0
	v_mov_b32_e32 v111, v0
	v_mov_b32_e32 v116, v0
	v_mov_b32_e32 v117, v0
	v_mov_b32_e32 v118, v0
	v_mov_b32_e32 v119, v0
	v_mov_b32_e32 v120, v0
	v_mov_b32_e32 v121, v0
	v_mov_b32_e32 v122, v0
	v_mov_b32_e32 v123, v0
	v_mov_b32_e32 v124, v0
	v_mov_b32_e32 v125, v0
	v_mov_b32_e32 v126, v0
	v_mov_b32_e32 v127, v0
	s_cmp_eq_u32 s90, 3
	s_cbranch_scc1 .LBB0_1832
	s_cmp_eq_u32 s90, 1
	s_cbranch_scc0 .Lts_b_h1
.Lts_b_h0:
	v_add_u32_e32 v128, s65, v155
	ds_read_b128 v[158:161], v128
	ds_read_b128 v[162:165], v128 offset:1024
	ds_read_b128 v[166:169], v128 offset:2048
	ds_read_b128 v[170:173], v128 offset:3072
	s_cmp_eq_u32 s44, 12
	v_lshl_add_u64 v[152:153], v[148:149], 0, s[22:23]
	s_cselect_b64 vcc, -1, 0
	v_cndmask_b32_e32 v207, v153, v147, vcc
	v_cndmask_b32_e32 v206, v152, v146, vcc
	v_cndmask_b32_e32 v153, v151, v145, vcc
	v_cndmask_b32_e32 v152, v150, v144, vcc
	v_lshl_add_u64 v[210:211], v[148:149], 0, v[134:135]
	s_add_i32 m0, s53, 0xc000
	ds_read_b128 v[174:177], v157
	ds_read_b128 v[178:181], v157 offset:1024
	ds_read_b128 v[182:185], v157 offset:2048
	ds_read_b128 v[186:189], v157 offset:3072
	ds_read_b128 v[190:193], v157 offset:4096
	ds_read_b128 v[194:197], v157 offset:5120
	ds_read_b128 v[198:201], v157 offset:6144
	ds_read_b128 v[202:205], v157 offset:7168
	global_load_lds_dwordx4 v[210:211], off
	v_lshl_add_u64 v[210:211], v[148:149], 0, v[136:137]
	s_add_i32 m0, s53, 0xe000
	s_nop 0
	global_load_lds_dwordx4 v[210:211], off
	s_waitcnt lgkmcnt(8)
	s_barrier
	s_waitcnt lgkmcnt(0)
	s_setprio 1
	s_waitcnt lgkmcnt(0)
	v_mfma_f32_16x16x32_bf16 v[124:127], v[158:161], v[174:177], v[124:127]
	v_mfma_f32_16x16x32_bf16 v[120:123], v[166:169], v[174:177], v[120:123]
	v_mfma_f32_16x16x32_bf16 v[116:119], v[158:161], v[182:185], v[116:119]
	v_mfma_f32_16x16x32_bf16 v[108:111], v[166:169], v[182:185], v[108:111]
	v_mfma_f32_16x16x32_bf16 v[100:103], v[158:161], v[190:193], v[100:103]
	v_mfma_f32_16x16x32_bf16 v[92:95], v[166:169], v[190:193], v[92:95]
	v_mfma_f32_16x16x32_bf16 v[84:87], v[158:161], v[198:201], v[84:87]
	v_mfma_f32_16x16x32_bf16 v[76:79], v[166:169], v[198:201], v[76:79]
	v_mfma_f32_16x16x32_bf16 v[124:127], v[162:165], v[178:181], v[124:127]
	v_mfma_f32_16x16x32_bf16 v[120:123], v[170:173], v[178:181], v[120:123]
	v_mfma_f32_16x16x32_bf16 v[116:119], v[162:165], v[186:189], v[116:119]
	v_mfma_f32_16x16x32_bf16 v[108:111], v[170:173], v[186:189], v[108:111]
	v_mfma_f32_16x16x32_bf16 v[100:103], v[162:165], v[194:197], v[100:103]
	v_mfma_f32_16x16x32_bf16 v[92:95], v[170:173], v[194:197], v[92:95]
	v_mfma_f32_16x16x32_bf16 v[84:87], v[162:165], v[202:205], v[84:87]
	v_mfma_f32_16x16x32_bf16 v[76:79], v[170:173], v[202:205], v[76:79]
	s_setprio 0
	s_barrier
	s_add_i32 s45, s65, s52
	v_add_u32_e32 v128, s66, v155
	v_lshl_add_u64 v[226:227], v[152:153], 0, v[130:131]
	s_mov_b32 m0, s45
	ds_read_b128 v[210:213], v128
	ds_read_b128 v[214:217], v128 offset:1024
	ds_read_b128 v[218:221], v128 offset:2048
	ds_read_b128 v[222:225], v128 offset:3072
	global_load_lds_dwordx4 v[226:227], off
	v_lshl_add_u64 v[228:229], v[152:153], 0, v[132:133]
	s_add_i32 m0, s45, 0x2000
	s_nop 0
	global_load_lds_dwordx4 v[228:229], off
	s_barrier
	s_waitcnt lgkmcnt(0)
	s_setprio 1
	s_waitcnt lgkmcnt(0)
	v_mfma_f32_16x16x32_bf16 v[112:115], v[210:213], v[174:177], v[112:115]
	v_mfma_f32_16x16x32_bf16 v[104:107], v[218:221], v[174:177], v[104:107]
	v_mfma_f32_16x16x32_bf16 v[96:99], v[210:213], v[182:185], v[96:99]
	v_mfma_f32_16x16x32_bf16 v[88:91], v[218:221], v[182:185], v[88:91]
	v_mfma_f32_16x16x32_bf16 v[80:83], v[210:213], v[190:193], v[80:83]
	v_mfma_f32_16x16x32_bf16 v[72:75], v[218:221], v[190:193], v[72:75]
	v_mfma_f32_16x16x32_bf16 v[68:71], v[210:213], v[198:201], v[68:71]
	v_mfma_f32_16x16x32_bf16 v[64:67], v[218:221], v[198:201], v[64:67]
	v_mfma_f32_16x16x32_bf16 v[112:115], v[214:217], v[178:181], v[112:115]
	v_mfma_f32_16x16x32_bf16 v[104:107], v[222:225], v[178:181], v[104:107]
	v_mfma_f32_16x16x32_bf16 v[96:99], v[214:217], v[186:189], v[96:99]
	v_mfma_f32_16x16x32_bf16 v[88:91], v[222:225], v[186:189], v[88:91]
	v_mfma_f32_16x16x32_bf16 v[80:83], v[214:217], v[194:197], v[80:83]
	v_mfma_f32_16x16x32_bf16 v[72:75], v[222:225], v[194:197], v[72:75]
	v_mfma_f32_16x16x32_bf16 v[68:71], v[214:217], v[202:205], v[68:71]
	v_mfma_f32_16x16x32_bf16 v[64:67], v[222:225], v[202:205], v[64:67]
	s_setprio 0
	s_mov_b32 m0, s53
	v_lshl_add_u64 v[230:231], v[206:207], 0, v[130:131]
	s_barrier
	s_nop 7
	global_load_lds_dwordx4 v[230:231], off
	v_lshl_add_u64 v[232:233], v[206:207], 0, v[132:133]
	s_mov_b32 m0, s54
	s_nop 0
	global_load_lds_dwordx4 v[232:233], off
	s_barrier
	s_waitcnt lgkmcnt(0)
	s_setprio 1
	s_waitcnt lgkmcnt(0)
	s_setprio 0
	s_barrier
	v_lshl_add_u64 v[158:159], v[152:153], 0, s[12:13]
	s_add_i32 s45, s66, s52
	v_lshl_add_u64 v[160:161], v[158:159], 0, v[130:131]
	s_mov_b32 m0, s45
	v_lshl_add_u64 v[158:159], v[158:159], 0, v[132:133]
	global_load_lds_dwordx4 v[160:161], off
	s_add_i32 m0, s45, 0x2000
	s_nop 0
	global_load_lds_dwordx4 v[158:159], off
	s_waitcnt vmcnt(6)
	s_barrier
	s_setprio 1
	s_setprio 0
	s_add_i32 s45, 0, 0x18000
	v_add_u32_e32 v128, s45, v155
	s_barrier
	ds_read_b128 v[158:161], v128
	ds_read_b128 v[162:165], v128 offset:1024
	ds_read_b128 v[166:169], v128 offset:2048
	ds_read_b128 v[170:173], v128 offset:3072
	v_lshl_add_u64 v[206:207], v[206:207], 0, s[12:13]
	s_mov_b32 m0, s55
	v_lshl_add_u64 v[210:211], v[206:207], 0, v[130:131]
	ds_read_b128 v[174:177], v157 offset:32768
	ds_read_b128 v[178:181], v157 offset:33792
	ds_read_b128 v[182:185], v157 offset:34816
	ds_read_b128 v[186:189], v157 offset:35840
	ds_read_b128 v[190:193], v157 offset:36864
	ds_read_b128 v[194:197], v157 offset:37888
	ds_read_b128 v[198:201], v157 offset:38912
	ds_read_b128 v[202:205], v157 offset:39936
	global_load_lds_dwordx4 v[210:211], off
	v_lshl_add_u64 v[206:207], v[206:207], 0, v[132:133]
	s_mov_b32 m0, s56
	s_nop 0
	global_load_lds_dwordx4 v[206:207], off
	s_waitcnt lgkmcnt(8)
	s_barrier
	s_waitcnt lgkmcnt(0)
	s_setprio 1
	s_waitcnt lgkmcnt(0)
	v_mfma_f32_16x16x32_bf16 v[124:127], v[158:161], v[174:177], v[124:127]
	v_mfma_f32_16x16x32_bf16 v[120:123], v[166:169], v[174:177], v[120:123]
	v_mfma_f32_16x16x32_bf16 v[116:119], v[158:161], v[182:185], v[116:119]
	v_mfma_f32_16x16x32_bf16 v[108:111], v[166:169], v[182:185], v[108:111]
	v_mfma_f32_16x16x32_bf16 v[100:103], v[158:161], v[190:193], v[100:103]
	v_mfma_f32_16x16x32_bf16 v[92:95], v[166:169], v[190:193], v[92:95]
	v_mfma_f32_16x16x32_bf16 v[84:87], v[158:161], v[198:201], v[84:87]
	v_mfma_f32_16x16x32_bf16 v[76:79], v[166:169], v[198:201], v[76:79]
	v_mfma_f32_16x16x32_bf16 v[124:127], v[162:165], v[178:181], v[124:127]
	v_mfma_f32_16x16x32_bf16 v[120:123], v[170:173], v[178:181], v[120:123]
	v_mfma_f32_16x16x32_bf16 v[116:119], v[162:165], v[186:189], v[116:119]
	v_mfma_f32_16x16x32_bf16 v[108:111], v[170:173], v[186:189], v[108:111]
	v_mfma_f32_16x16x32_bf16 v[100:103], v[162:165], v[194:197], v[100:103]
	v_mfma_f32_16x16x32_bf16 v[92:95], v[170:173], v[194:197], v[92:95]
	v_mfma_f32_16x16x32_bf16 v[84:87], v[162:165], v[202:205], v[84:87]
	v_mfma_f32_16x16x32_bf16 v[76:79], v[170:173], v[202:205], v[76:79]
	s_setprio 0
	s_barrier
	s_add_i32 s75, 0, 0x1c000
	s_add_i32 s45, s45, s52
	v_add_u32_e32 v128, s75, v155
	v_lshl_add_u64 v[206:207], v[226:227], 0, s[16:17]
	s_mov_b32 m0, s45
	ds_read_b128 v[210:213], v128
	ds_read_b128 v[214:217], v128 offset:1024
	ds_read_b128 v[218:221], v128 offset:2048
	ds_read_b128 v[222:225], v128 offset:3072
	global_load_lds_dwordx4 v[206:207], off
	v_lshl_add_u64 v[206:207], v[228:229], 0, s[16:17]
	s_add_i32 m0, s45, 0x2000
	s_nop 0
	global_load_lds_dwordx4 v[206:207], off
	s_barrier
	s_waitcnt lgkmcnt(0)
	s_setprio 1
	s_waitcnt lgkmcnt(0)
	v_mfma_f32_16x16x32_bf16 v[112:115], v[210:213], v[174:177], v[112:115]
	v_mfma_f32_16x16x32_bf16 v[104:107], v[218:221], v[174:177], v[104:107]
	v_mfma_f32_16x16x32_bf16 v[96:99], v[210:213], v[182:185], v[96:99]
	v_mfma_f32_16x16x32_bf16 v[88:91], v[218:221], v[182:185], v[88:91]
	v_mfma_f32_16x16x32_bf16 v[80:83], v[210:213], v[190:193], v[80:83]
	v_mfma_f32_16x16x32_bf16 v[72:75], v[218:221], v[190:193], v[72:75]
	v_mfma_f32_16x16x32_bf16 v[68:71], v[210:213], v[198:201], v[68:71]
	v_mfma_f32_16x16x32_bf16 v[64:67], v[218:221], v[198:201], v[64:67]
	v_mfma_f32_16x16x32_bf16 v[112:115], v[214:217], v[178:181], v[112:115]
	v_mfma_f32_16x16x32_bf16 v[104:107], v[222:225], v[178:181], v[104:107]
	v_mfma_f32_16x16x32_bf16 v[96:99], v[214:217], v[186:189], v[96:99]
	v_mfma_f32_16x16x32_bf16 v[88:91], v[222:225], v[186:189], v[88:91]
	v_mfma_f32_16x16x32_bf16 v[80:83], v[214:217], v[194:197], v[80:83]
	v_mfma_f32_16x16x32_bf16 v[72:75], v[222:225], v[194:197], v[72:75]
	v_mfma_f32_16x16x32_bf16 v[68:71], v[214:217], v[202:205], v[68:71]
	v_mfma_f32_16x16x32_bf16 v[64:67], v[222:225], v[202:205], v[64:67]
	s_setprio 0
	s_mov_b32 m0, s59
	v_lshl_add_u64 v[206:207], v[230:231], 0, s[16:17]
	s_barrier
	s_nop 7
	global_load_lds_dwordx4 v[206:207], off
	v_lshl_add_u64 v[206:207], v[232:233], 0, s[16:17]
	s_mov_b32 m0, s60
	s_nop 0
	global_load_lds_dwordx4 v[206:207], off
	s_barrier
	s_waitcnt lgkmcnt(0)
	s_setprio 1
	s_waitcnt lgkmcnt(0)
	s_setprio 0
	s_barrier
	v_lshl_add_u64 v[152:153], v[152:153], 0, s[18:19]
	s_add_i32 s45, s75, s52
	v_lshl_add_u64 v[158:159], v[152:153], 0, v[130:131]
	s_mov_b32 m0, s45
	v_lshl_add_u64 v[152:153], v[152:153], 0, v[132:133]
	global_load_lds_dwordx4 v[158:159], off
	s_add_i32 m0, s45, 0x2000
	s_nop 0
	global_load_lds_dwordx4 v[152:153], off
	s_waitcnt vmcnt(6)
	s_barrier
	s_setprio 1
	s_setprio 0
	s_add_i32 s44, s44, 2
	v_lshl_add_u64 v[148:149], v[148:149], 0, s[20:21]
	s_cmp_gt_u32 s44, 13
	v_lshl_add_u64 v[150:151], v[150:151], 0, s[20:21]
	s_barrier
	s_cbranch_scc0 .Lts_b_h0
	s_branch .Lts_b_x
.Lts_b_h1:
	v_add_u32_e32 v128, s65, v155
	ds_read_b128 v[158:161], v128
	ds_read_b128 v[162:165], v128 offset:1024
	ds_read_b128 v[166:169], v128 offset:2048
	ds_read_b128 v[170:173], v128 offset:3072
	s_cmp_eq_u32 s44, 12
	v_lshl_add_u64 v[152:153], v[148:149], 0, s[22:23]
	s_cselect_b64 vcc, -1, 0
	v_cndmask_b32_e32 v207, v153, v147, vcc
	v_cndmask_b32_e32 v206, v152, v146, vcc
	v_cndmask_b32_e32 v153, v151, v145, vcc
	v_cndmask_b32_e32 v152, v150, v144, vcc
	v_lshl_add_u64 v[210:211], v[148:149], 0, v[134:135]
	s_add_i32 m0, s53, 0xc000
	s_nop 7
	global_load_lds_dwordx4 v[210:211], off
	v_lshl_add_u64 v[210:211], v[148:149], 0, v[136:137]
	s_add_i32 m0, s53, 0xe000
	s_nop 0
	global_load_lds_dwordx4 v[210:211], off
	s_waitcnt lgkmcnt(8)
	s_barrier
	s_waitcnt lgkmcnt(0)
	s_setprio 1
	s_waitcnt lgkmcnt(0)
	s_setprio 0
	s_barrier
	s_add_i32 s45, s65, s52
	v_add_u32_e32 v128, s66, v155
	v_lshl_add_u64 v[226:227], v[152:153], 0, v[130:131]
	s_mov_b32 m0, s45
	ds_read_b128 v[210:213], v128
	ds_read_b128 v[214:217], v128 offset:1024
	ds_read_b128 v[218:221], v128 offset:2048
	ds_read_b128 v[222:225], v128 offset:3072
	global_load_lds_dwordx4 v[226:227], off
	v_lshl_add_u64 v[228:229], v[152:153], 0, v[132:133]
	s_add_i32 m0, s45, 0x2000
	s_nop 0
	global_load_lds_dwordx4 v[228:229], off
	s_barrier
	s_waitcnt lgkmcnt(0)
	s_setprio 1
	s_waitcnt lgkmcnt(0)
	s_setprio 0
	s_mov_b32 m0, s53
	v_lshl_add_u64 v[230:231], v[206:207], 0, v[130:131]
	s_barrier
	ds_read_b128 v[174:177], v157 offset:16384
	ds_read_b128 v[178:181], v157 offset:17408
	ds_read_b128 v[182:185], v157 offset:18432
	ds_read_b128 v[186:189], v157 offset:19456
	ds_read_b128 v[190:193], v157 offset:20480
	ds_read_b128 v[194:197], v157 offset:21504
	ds_read_b128 v[198:201], v157 offset:22528
	ds_read_b128 v[202:205], v157 offset:23552
	global_load_lds_dwordx4 v[230:231], off
	v_lshl_add_u64 v[232:233], v[206:207], 0, v[132:133]
	s_mov_b32 m0, s54
	s_nop 0
	global_load_lds_dwordx4 v[232:233], off
	s_barrier
	s_waitcnt lgkmcnt(0)
	s_setprio 1
	s_waitcnt lgkmcnt(0)
	v_mfma_f32_16x16x32_bf16 v[60:63], v[158:161], v[174:177], v[60:63]
	v_mfma_f32_16x16x32_bf16 v[56:59], v[166:169], v[174:177], v[56:59]
	v_mfma_f32_16x16x32_bf16 v[52:55], v[158:161], v[182:185], v[52:55]
	v_mfma_f32_16x16x32_bf16 v[44:47], v[166:169], v[182:185], v[44:47]
	v_mfma_f32_16x16x32_bf16 v[36:39], v[158:161], v[190:193], v[36:39]
	v_mfma_f32_16x16x32_bf16 v[28:31], v[166:169], v[190:193], v[28:31]
	v_mfma_f32_16x16x32_bf16 v[20:23], v[158:161], v[198:201], v[20:23]
	v_mfma_f32_16x16x32_bf16 v[12:15], v[166:169], v[198:201], v[12:15]
	v_mfma_f32_16x16x32_bf16 v[60:63], v[162:165], v[178:181], v[60:63]
	v_mfma_f32_16x16x32_bf16 v[56:59], v[170:173], v[178:181], v[56:59]
	v_mfma_f32_16x16x32_bf16 v[52:55], v[162:165], v[186:189], v[52:55]
	v_mfma_f32_16x16x32_bf16 v[44:47], v[170:173], v[186:189], v[44:47]
	v_mfma_f32_16x16x32_bf16 v[36:39], v[162:165], v[194:197], v[36:39]
	v_mfma_f32_16x16x32_bf16 v[28:31], v[170:173], v[194:197], v[28:31]
	v_mfma_f32_16x16x32_bf16 v[20:23], v[162:165], v[202:205], v[20:23]
	v_mfma_f32_16x16x32_bf16 v[12:15], v[170:173], v[202:205], v[12:15]
	s_setprio 0
	s_barrier
	v_lshl_add_u64 v[158:159], v[152:153], 0, s[12:13]
	s_add_i32 s45, s66, s52
	v_lshl_add_u64 v[160:161], v[158:159], 0, v[130:131]
	s_mov_b32 m0, s45
	v_lshl_add_u64 v[158:159], v[158:159], 0, v[132:133]
	global_load_lds_dwordx4 v[160:161], off
	s_add_i32 m0, s45, 0x2000
	s_nop 0
	global_load_lds_dwordx4 v[158:159], off
	s_waitcnt vmcnt(6)
	s_barrier
	s_setprio 1
	v_mfma_f32_16x16x32_bf16 v[48:51], v[210:213], v[174:177], v[48:51]
	v_mfma_f32_16x16x32_bf16 v[40:43], v[218:221], v[174:177], v[40:43]
	v_mfma_f32_16x16x32_bf16 v[32:35], v[210:213], v[182:185], v[32:35]
	v_mfma_f32_16x16x32_bf16 v[24:27], v[218:221], v[182:185], v[24:27]
	v_mfma_f32_16x16x32_bf16 v[16:19], v[210:213], v[190:193], v[16:19]
	v_mfma_f32_16x16x32_bf16 v[8:11], v[218:221], v[190:193], v[8:11]
	v_mfma_f32_16x16x32_bf16 v[4:7], v[210:213], v[198:201], v[4:7]
	v_mfma_f32_16x16x32_bf16 v[0:3], v[218:221], v[198:201], v[0:3]
	v_mfma_f32_16x16x32_bf16 v[48:51], v[214:217], v[178:181], v[48:51]
	v_mfma_f32_16x16x32_bf16 v[40:43], v[222:225], v[178:181], v[40:43]
	v_mfma_f32_16x16x32_bf16 v[32:35], v[214:217], v[186:189], v[32:35]
	v_mfma_f32_16x16x32_bf16 v[24:27], v[222:225], v[186:189], v[24:27]
	v_mfma_f32_16x16x32_bf16 v[16:19], v[214:217], v[194:197], v[16:19]
	v_mfma_f32_16x16x32_bf16 v[8:11], v[222:225], v[194:197], v[8:11]
	v_mfma_f32_16x16x32_bf16 v[4:7], v[214:217], v[202:205], v[4:7]
	v_mfma_f32_16x16x32_bf16 v[0:3], v[222:225], v[202:205], v[0:3]
	s_setprio 0
	s_add_i32 s45, 0, 0x18000
	v_add_u32_e32 v128, s45, v155
	s_barrier
	ds_read_b128 v[158:161], v128
	ds_read_b128 v[162:165], v128 offset:1024
	ds_read_b128 v[166:169], v128 offset:2048
	ds_read_b128 v[170:173], v128 offset:3072
	v_lshl_add_u64 v[206:207], v[206:207], 0, s[12:13]
	s_mov_b32 m0, s55
	v_lshl_add_u64 v[210:211], v[206:207], 0, v[130:131]
	s_nop 7
	global_load_lds_dwordx4 v[210:211], off
	v_lshl_add_u64 v[206:207], v[206:207], 0, v[132:133]
	s_mov_b32 m0, s56
	s_nop 0
	global_load_lds_dwordx4 v[206:207], off
	s_waitcnt lgkmcnt(8)
	s_barrier
	s_waitcnt lgkmcnt(0)
	s_setprio 1
	s_waitcnt lgkmcnt(0)
	s_setprio 0
	s_barrier
	s_add_i32 s75, 0, 0x1c000
	s_add_i32 s45, s45, s52
	v_add_u32_e32 v128, s75, v155
	v_lshl_add_u64 v[206:207], v[226:227], 0, s[16:17]
	s_mov_b32 m0, s45
	ds_read_b128 v[210:213], v128
	ds_read_b128 v[214:217], v128 offset:1024
	ds_read_b128 v[218:221], v128 offset:2048
	ds_read_b128 v[222:225], v128 offset:3072
	global_load_lds_dwordx4 v[206:207], off
	v_lshl_add_u64 v[206:207], v[228:229], 0, s[16:17]
	s_add_i32 m0, s45, 0x2000
	s_nop 0
	global_load_lds_dwordx4 v[206:207], off
	s_barrier
	s_waitcnt lgkmcnt(0)
	s_setprio 1
	s_waitcnt lgkmcnt(0)
	s_setprio 0
	s_mov_b32 m0, s59
	v_lshl_add_u64 v[206:207], v[230:231], 0, s[16:17]
	s_barrier
	ds_read_b128 v[174:177], v157 offset:49152
	ds_read_b128 v[178:181], v157 offset:50176
	ds_read_b128 v[182:185], v157 offset:51200
	ds_read_b128 v[186:189], v157 offset:52224
	ds_read_b128 v[190:193], v157 offset:53248
	ds_read_b128 v[194:197], v157 offset:54272
	ds_read_b128 v[198:201], v157 offset:55296
	ds_read_b128 v[202:205], v157 offset:56320
	global_load_lds_dwordx4 v[206:207], off
	v_lshl_add_u64 v[206:207], v[232:233], 0, s[16:17]
	s_mov_b32 m0, s60
	s_nop 0
	global_load_lds_dwordx4 v[206:207], off
	s_barrier
	s_waitcnt lgkmcnt(0)
	s_setprio 1
	s_waitcnt lgkmcnt(0)
	v_mfma_f32_16x16x32_bf16 v[60:63], v[158:161], v[174:177], v[60:63]
	v_mfma_f32_16x16x32_bf16 v[56:59], v[166:169], v[174:177], v[56:59]
	v_mfma_f32_16x16x32_bf16 v[52:55], v[158:161], v[182:185], v[52:55]
	v_mfma_f32_16x16x32_bf16 v[44:47], v[166:169], v[182:185], v[44:47]
	v_mfma_f32_16x16x32_bf16 v[36:39], v[158:161], v[190:193], v[36:39]
	v_mfma_f32_16x16x32_bf16 v[28:31], v[166:169], v[190:193], v[28:31]
	v_mfma_f32_16x16x32_bf16 v[20:23], v[158:161], v[198:201], v[20:23]
	v_mfma_f32_16x16x32_bf16 v[12:15], v[166:169], v[198:201], v[12:15]
	v_mfma_f32_16x16x32_bf16 v[60:63], v[162:165], v[178:181], v[60:63]
	v_mfma_f32_16x16x32_bf16 v[56:59], v[170:173], v[178:181], v[56:59]
	v_mfma_f32_16x16x32_bf16 v[52:55], v[162:165], v[186:189], v[52:55]
	v_mfma_f32_16x16x32_bf16 v[44:47], v[170:173], v[186:189], v[44:47]
	v_mfma_f32_16x16x32_bf16 v[36:39], v[162:165], v[194:197], v[36:39]
	v_mfma_f32_16x16x32_bf16 v[28:31], v[170:173], v[194:197], v[28:31]
	v_mfma_f32_16x16x32_bf16 v[20:23], v[162:165], v[202:205], v[20:23]
	v_mfma_f32_16x16x32_bf16 v[12:15], v[170:173], v[202:205], v[12:15]
	s_setprio 0
	s_barrier
	v_lshl_add_u64 v[152:153], v[152:153], 0, s[18:19]
	s_add_i32 s45, s75, s52
	v_lshl_add_u64 v[158:159], v[152:153], 0, v[130:131]
	s_mov_b32 m0, s45
	v_lshl_add_u64 v[152:153], v[152:153], 0, v[132:133]
	global_load_lds_dwordx4 v[158:159], off
	s_add_i32 m0, s45, 0x2000
	s_nop 0
	global_load_lds_dwordx4 v[152:153], off
	s_waitcnt vmcnt(6)
	s_barrier
	s_setprio 1
	v_mfma_f32_16x16x32_bf16 v[48:51], v[210:213], v[174:177], v[48:51]
	v_mfma_f32_16x16x32_bf16 v[40:43], v[218:221], v[174:177], v[40:43]
	v_mfma_f32_16x16x32_bf16 v[32:35], v[210:213], v[182:185], v[32:35]
	v_mfma_f32_16x16x32_bf16 v[24:27], v[218:221], v[182:185], v[24:27]
	v_mfma_f32_16x16x32_bf16 v[16:19], v[210:213], v[190:193], v[16:19]
	v_mfma_f32_16x16x32_bf16 v[8:11], v[218:221], v[190:193], v[8:11]
	v_mfma_f32_16x16x32_bf16 v[4:7], v[210:213], v[198:201], v[4:7]
	v_mfma_f32_16x16x32_bf16 v[0:3], v[218:221], v[198:201], v[0:3]
	v_mfma_f32_16x16x32_bf16 v[48:51], v[214:217], v[178:181], v[48:51]
	v_mfma_f32_16x16x32_bf16 v[40:43], v[222:225], v[178:181], v[40:43]
	v_mfma_f32_16x16x32_bf16 v[32:35], v[214:217], v[186:189], v[32:35]
	v_mfma_f32_16x16x32_bf16 v[24:27], v[222:225], v[186:189], v[24:27]
	v_mfma_f32_16x16x32_bf16 v[16:19], v[214:217], v[194:197], v[16:19]
	v_mfma_f32_16x16x32_bf16 v[8:11], v[222:225], v[194:197], v[8:11]
	v_mfma_f32_16x16x32_bf16 v[4:7], v[214:217], v[202:205], v[4:7]
	v_mfma_f32_16x16x32_bf16 v[0:3], v[222:225], v[202:205], v[0:3]
	s_setprio 0
	s_add_i32 s44, s44, 2
	v_lshl_add_u64 v[148:149], v[148:149], 0, s[20:21]
	s_cmp_gt_u32 s44, 13
	v_lshl_add_u64 v[150:151], v[150:151], 0, s[20:21]
	s_barrier
	s_cbranch_scc0 .Lts_b_h1
	s_branch .Lts_b_x
